# stack13 with 16 of the gate stores write-through but without nt (allow infinity-cache allocation)
# baseline (speedup 1.0000x reference)
; __device__ __forceinline__ unsigned pk2(float lo, float hi) { f32v2 v = {lo, hi}; bf16v2 r = __builtin_convertvector(v, bf16v2); return __builtin_bit_cast(unsigned, r); }
; __device__ __forceinline__ float sigmoid_f(float x) { return __builtin_amdgcn_rcpf(1.0f + __builtin_amdgcn_exp2f(-1.4426950409f * x)); }
;     __device__ __forceinline__ void operator()(f32x4 (&acc)[2][2][4][2], const Unit& u, int wr, int wc, int fr, int fq) const {
;     ...
;             if (u.pn >= 6 && u.pn < 14) {
;                 const int chb = 128 * (u.pn - 6) + cl0;
; #pragma unroll
;                 for (int ai = 0; ai < 2; ++ai)
; #pragma unroll
;                     for (int m = 0; m < 4; ++m) {
;                         const size_t row = (size_t)(row0 + ai * HALF + m * 16);
;                         float r[8], g[8];
; #pragma unroll
;                         for (int e = 0; e < 4; ++e) {
;                             const float g0a = fmaxf(sigmoid_f(acc[ai][0][m][0][e]), 1e-13f), g0b = fmaxf(sigmoid_f(acc[ai][0][m][1][e]), 1e-13f);
;                             const float g1a = fmaxf(sigmoid_f(acc[ai][1][m][0][e]), 1e-13f), g1b = fmaxf(sigmoid_f(acc[ai][1][m][1][e]), 1e-13f);
;                             g[e] = g1a; g[4 + e] = g1b; r[e] = g0a * __builtin_amdgcn_rcpf(g1a); r[4 + e] = g0b * __builtin_amdgcn_rcpf(g1b);
;                         }
;                         u32x4 wr_, wg_; wr_.x = pk2(r[0], r[1]); wr_.y = pk2(r[2], r[3]); wr_.z = pk2(r[4], r[5]); wr_.w = pk2(r[6], r[7]);
;                         wg_.x = pk2(g[0], g[1]); wg_.y = pk2(g[2], g[3]); wg_.z = pk2(g[4], g[5]); wg_.w = pk2(g[6], g[7]);
;                         __builtin_nontemporal_store(wr_, (u32x4*)(O4 + row * 3072 + chb));
;                         __builtin_nontemporal_store(wg_, (u32x4*)(O4 + row * 3072 + 1024 + chb));
;                     }
.LBB0_558:
	s_and_b64 vcc, exec, s[6:7]
	s_cbranch_vccz .LBB0_560
	v_mul_f32_e32 v129, 0xbfb8aa3b, v120
	v_exp_f32_e32 v129, v129
	v_mul_f32_e32 v133, 0xbfb8aa3b, v117
	v_exp_f32_e32 v133, v133
	v_mul_f32_e32 v128, 0xbfb8aa3b, v124
	v_add_f32_e32 v129, 1.0, v129
	v_rcp_f32_e32 v129, v129
	v_add_f32_e32 v133, 1.0, v133
	v_rcp_f32_e32 v133, v133
	v_exp_f32_e32 v128, v128
	v_max_f32_e32 v130, 0x29e12e13, v129
	v_mul_f32_e32 v129, 0xbfb8aa3b, v116
	v_exp_f32_e32 v129, v129
	v_max_f32_e32 v153, 0x29e12e13, v133
	v_mul_f32_e32 v133, 0xbfb8aa3b, v113
	v_exp_f32_e32 v133, v133
	v_add_f32_e32 v129, 1.0, v129
	v_rcp_f32_e32 v129, v129
	v_add_f32_e32 v128, 1.0, v128
	v_add_f32_e32 v133, 1.0, v133
	v_rcp_f32_e32 v133, v133
	v_max_f32_e32 v147, 0x29e12e13, v129
	v_mul_f32_e32 v129, 0xbfb8aa3b, v112
	v_exp_f32_e32 v129, v129
	v_rcp_f32_e32 v128, v128
	v_rcp_f32_e32 v132, v147
	v_max_f32_e32 v154, 0x29e12e13, v133
	v_add_f32_e32 v129, 1.0, v129
	v_rcp_f32_e32 v129, v129
	v_rcp_f32_e32 v133, v153
	v_max_f32_e32 v128, 0x29e12e13, v128
	v_mul_f32_e32 v131, 0xbfb8aa3b, v121
	v_max_f32_e32 v152, 0x29e12e13, v129
	v_mul_f32_e32 v129, 0xbfb8aa3b, v125
	v_exp_f32_e32 v129, v129
	v_exp_f32_e32 v131, v131
	v_rcp_f32_e32 v134, v152
	v_rcp_f32_e32 v135, v154
	v_add_f32_e32 v129, 1.0, v129
	v_rcp_f32_e32 v129, v129
	v_add_f32_e32 v131, 1.0, v131
	v_rcp_f32_e32 v131, v131
	v_mul_f32_e32 v149, 0xbfb8aa3b, v119
	v_max_f32_e32 v129, 0x29e12e13, v129
	v_pk_mul_f32 v[128:129], v[132:133], v[128:129]
	v_mul_f32_e32 v133, 0xbfb8aa3b, v122
	v_exp_f32_e32 v133, v133
	v_max_f32_e32 v131, 0x29e12e13, v131
	v_pk_mul_f32 v[130:131], v[134:135], v[130:131]
	v_exp_f32_e32 v149, v149
	v_add_f32_e32 v133, 1.0, v133
	v_rcp_f32_e32 v133, v133
	v_mul_f32_e32 v132, 0xbfb8aa3b, v126
	v_add_f32_e32 v149, 1.0, v149
	v_rcp_f32_e32 v149, v149
	v_max_f32_e32 v134, 0x29e12e13, v133
	v_mul_f32_e32 v133, 0xbfb8aa3b, v118
	v_exp_f32_e32 v133, v133
	v_max_f32_e32 v157, 0x29e12e13, v149
	v_mul_f32_e32 v149, 0xbfb8aa3b, v115
	v_exp_f32_e32 v149, v149
	v_add_f32_e32 v133, 1.0, v133
	v_rcp_f32_e32 v133, v133
	v_mul_f32_e32 v135, 0xbfb8aa3b, v123
	v_exp_f32_e32 v132, v132
	v_exp_f32_e32 v135, v135
	v_max_f32_e32 v155, 0x29e12e13, v133
	v_mul_f32_e32 v133, 0xbfb8aa3b, v114
	v_exp_f32_e32 v133, v133
	v_add_f32_e32 v149, 1.0, v149
	v_rcp_f32_e32 v149, v149
	v_add_f32_e32 v132, 1.0, v132
	v_add_f32_e32 v133, 1.0, v133
	v_rcp_f32_e32 v133, v133
	v_add_f32_e32 v135, 1.0, v135
	v_rcp_f32_e32 v132, v132
	v_rcp_f32_e32 v135, v135
	v_max_f32_e32 v156, 0x29e12e13, v133
	v_mul_f32_e32 v133, 0xbfb8aa3b, v127
	v_exp_f32_e32 v133, v133
	v_max_f32_e32 v158, 0x29e12e13, v149
	v_rcp_f32_e32 v148, v155
	v_rcp_f32_e32 v150, v156
	v_add_f32_e32 v133, 1.0, v133
	v_rcp_f32_e32 v133, v133
	v_rcp_f32_e32 v149, v157
	v_rcp_f32_e32 v151, v158
	v_readlane_b32 s6, v253, 24
	v_max_f32_e32 v132, 0x29e12e13, v132
	v_max_f32_e32 v133, 0x29e12e13, v133
	v_max_f32_e32 v135, 0x29e12e13, v135
	v_readlane_b32 s7, v253, 25
	v_lshl_add_u32 v178, s70, 7, v163
	v_pk_mul_f32 v[148:149], v[148:149], v[132:133]
	v_pk_mul_f32 v[150:151], v[150:151], v[134:135]
	v_cvt_pk_bf16_f32 v132, v128, v129
	v_mov_b64_e32 v[128:129], s[6:7]
	v_cvt_pk_bf16_f32 v133, v148, v149
	v_cvt_pk_bf16_f32 v134, v130, v131
	v_cvt_pk_bf16_f32 v135, v150, v151
	v_cvt_pk_bf16_f32 v148, v147, v153
	v_cvt_pk_bf16_f32 v150, v152, v154
	v_mad_i64_i32 v[152:153], s[6:7], v146, s33, v[128:129]
	v_lshlrev_b64 v[130:131], 1, v[178:179]
	v_lshl_add_u64 v[152:153], v[152:153], 0, v[130:131]
	v_cvt_pk_bf16_f32 v149, v155, v157
	v_cvt_pk_bf16_f32 v151, v156, v158
	global_store_dwordx4 v[152:153], v[132:135], off sc0 sc1
	global_store_dwordx4 v[152:153], v[148:151], off offset:2048 sc0 sc1
	v_mul_f32_e32 v153, 0xbfb8aa3b, v103
	v_mul_f32_e32 v133, 0xbfb8aa3b, v104
	v_exp_f32_e32 v133, v133
	v_mul_f32_e32 v149, 0xbfb8aa3b, v101
	v_exp_f32_e32 v149, v149
	v_mul_f32_e32 v132, 0xbfb8aa3b, v108
	v_add_f32_e32 v133, 1.0, v133
	v_rcp_f32_e32 v133, v133
	v_add_f32_e32 v149, 1.0, v149
	v_rcp_f32_e32 v149, v149
	v_exp_f32_e32 v132, v132
	v_max_f32_e32 v134, 0x29e12e13, v133
	v_mul_f32_e32 v133, 0xbfb8aa3b, v100
	v_exp_f32_e32 v133, v133
	v_max_f32_e32 v158, 0x29e12e13, v149
	v_mul_f32_e32 v149, 0xbfb8aa3b, v97
	v_exp_f32_e32 v149, v149
	v_add_f32_e32 v133, 1.0, v133
	v_rcp_f32_e32 v133, v133
	v_add_f32_e32 v132, 1.0, v132
	v_add_f32_e32 v149, 1.0, v149
	v_rcp_f32_e32 v149, v149
	v_max_f32_e32 v156, 0x29e12e13, v133
	v_mul_f32_e32 v133, 0xbfb8aa3b, v96
	v_exp_f32_e32 v133, v133
	v_rcp_f32_e32 v132, v132
	v_rcp_f32_e32 v148, v156
	v_max_f32_e32 v159, 0x29e12e13, v149
	v_add_f32_e32 v133, 1.0, v133
	v_rcp_f32_e32 v133, v133
	v_rcp_f32_e32 v149, v158
	v_max_f32_e32 v132, 0x29e12e13, v132
	v_mul_f32_e32 v135, 0xbfb8aa3b, v105
	v_max_f32_e32 v157, 0x29e12e13, v133
	v_mul_f32_e32 v133, 0xbfb8aa3b, v109
	v_exp_f32_e32 v133, v133
	v_exp_f32_e32 v135, v135
	v_rcp_f32_e32 v150, v157
	v_rcp_f32_e32 v151, v159
	v_add_f32_e32 v133, 1.0, v133
	v_rcp_f32_e32 v133, v133
	v_add_f32_e32 v135, 1.0, v135
	v_rcp_f32_e32 v135, v135
	v_exp_f32_e32 v153, v153
	v_max_f32_e32 v133, 0x29e12e13, v133
	v_pk_mul_f32 v[132:133], v[148:149], v[132:133]
	v_mul_f32_e32 v149, 0xbfb8aa3b, v106
	v_exp_f32_e32 v149, v149
	v_max_f32_e32 v135, 0x29e12e13, v135
	v_pk_mul_f32 v[134:135], v[150:151], v[134:135]
	v_add_f32_e32 v153, 1.0, v153
	v_add_f32_e32 v149, 1.0, v149
	v_rcp_f32_e32 v149, v149
	v_rcp_f32_e32 v153, v153
	v_mul_f32_e32 v148, 0xbfb8aa3b, v110
	v_mul_f32_e32 v151, 0xbfb8aa3b, v107
	v_max_f32_e32 v150, 0x29e12e13, v149
	v_mul_f32_e32 v149, 0xbfb8aa3b, v102
	v_exp_f32_e32 v149, v149
	v_max_f32_e32 v166, 0x29e12e13, v153
; __device__ __forceinline__ unsigned pk2(float lo, float hi) { f32v2 v = {lo, hi}; bf16v2 r = __builtin_convertvector(v, bf16v2); return __builtin_bit_cast(unsigned, r); }
; __device__ __forceinline__ float sigmoid_f(float x) { return __builtin_amdgcn_rcpf(1.0f + __builtin_amdgcn_exp2f(-1.4426950409f * x)); }
;     __device__ __forceinline__ void operator()(f32x4 (&acc)[2][2][4][2], const Unit& u, int wr, int wc, int fr, int fq) const {
;     ...
;             if (u.pn >= 6 && u.pn < 14) {
;                 const int chb = 128 * (u.pn - 6) + cl0;
; #pragma unroll
;                 for (int ai = 0; ai < 2; ++ai)
; #pragma unroll
;                     for (int m = 0; m < 4; ++m) {
;                         const size_t row = (size_t)(row0 + ai * HALF + m * 16);
;                         float r[8], g[8];
; #pragma unroll
;                         for (int e = 0; e < 4; ++e) {
;                             const float g0a = fmaxf(sigmoid_f(acc[ai][0][m][0][e]), 1e-13f), g0b = fmaxf(sigmoid_f(acc[ai][0][m][1][e]), 1e-13f);
;                             const float g1a = fmaxf(sigmoid_f(acc[ai][1][m][0][e]), 1e-13f), g1b = fmaxf(sigmoid_f(acc[ai][1][m][1][e]), 1e-13f);
;                             g[e] = g1a; g[4 + e] = g1b; r[e] = g0a * __builtin_amdgcn_rcpf(g1a); r[4 + e] = g0b * __builtin_amdgcn_rcpf(g1b);
;                         }
;                         u32x4 wr_, wg_; wr_.x = pk2(r[0], r[1]); wr_.y = pk2(r[2], r[3]); wr_.z = pk2(r[4], r[5]); wr_.w = pk2(r[6], r[7]);
;                         wg_.x = pk2(g[0], g[1]); wg_.y = pk2(g[2], g[3]); wg_.z = pk2(g[4], g[5]); wg_.w = pk2(g[6], g[7]);
;                         __builtin_nontemporal_store(wr_, (u32x4*)(O4 + row * 3072 + chb));
;                         __builtin_nontemporal_store(wg_, (u32x4*)(O4 + row * 3072 + 1024 + chb));
;                     }
	v_mul_f32_e32 v153, 0xbfb8aa3b, v99
	v_exp_f32_e32 v153, v153
	v_add_f32_e32 v149, 1.0, v149
	v_rcp_f32_e32 v149, v149
	v_exp_f32_e32 v148, v148
	v_exp_f32_e32 v151, v151
	v_add_f32_e32 v153, 1.0, v153
	v_max_f32_e32 v160, 0x29e12e13, v149
	v_mul_f32_e32 v149, 0xbfb8aa3b, v98
	v_exp_f32_e32 v149, v149
	v_rcp_f32_e32 v153, v153
	v_add_f32_e32 v148, 1.0, v148
	v_add_f32_e32 v151, 1.0, v151
	v_add_f32_e32 v149, 1.0, v149
	v_rcp_f32_e32 v149, v149
	v_rcp_f32_e32 v148, v148
	v_rcp_f32_e32 v151, v151
	v_max_f32_e32 v167, 0x29e12e13, v153
	v_max_f32_e32 v161, 0x29e12e13, v149
	v_mul_f32_e32 v149, 0xbfb8aa3b, v111
	v_exp_f32_e32 v149, v149
	v_rcp_f32_e32 v152, v160
	v_rcp_f32_e32 v154, v161
	v_rcp_f32_e32 v153, v166
	v_add_f32_e32 v149, 1.0, v149
	v_rcp_f32_e32 v149, v149
	v_rcp_f32_e32 v155, v167
	v_or_b32_e32 v147, 16, v146
	v_max_f32_e32 v148, 0x29e12e13, v148
	v_max_f32_e32 v149, 0x29e12e13, v149
	v_max_f32_e32 v151, 0x29e12e13, v151
	v_pk_mul_f32 v[148:149], v[152:153], v[148:149]
	v_pk_mul_f32 v[150:151], v[154:155], v[150:151]
	v_mad_i64_i32 v[152:153], s[6:7], v147, s33, v[128:129]
	v_cvt_pk_bf16_f32 v132, v132, v133
	v_cvt_pk_bf16_f32 v133, v148, v149
	v_cvt_pk_bf16_f32 v134, v134, v135
	v_cvt_pk_bf16_f32 v135, v150, v151
	v_lshl_add_u64 v[152:153], v[152:153], 0, v[130:131]
	v_cvt_pk_bf16_f32 v148, v156, v158
	v_cvt_pk_bf16_f32 v149, v160, v166
	v_cvt_pk_bf16_f32 v150, v157, v159
	v_cvt_pk_bf16_f32 v151, v161, v167
	global_store_dwordx4 v[152:153], v[132:135], off sc0 sc1
	global_store_dwordx4 v[152:153], v[148:151], off offset:2048 sc0 sc1
	v_mul_f32_e32 v153, 0xbfb8aa3b, v87
	v_mul_f32_e32 v133, 0xbfb8aa3b, v88
	v_exp_f32_e32 v133, v133
	v_mul_f32_e32 v149, 0xbfb8aa3b, v85
	v_exp_f32_e32 v149, v149
	v_mul_f32_e32 v132, 0xbfb8aa3b, v92
	v_add_f32_e32 v133, 1.0, v133
	v_rcp_f32_e32 v133, v133
	v_add_f32_e32 v149, 1.0, v149
	v_rcp_f32_e32 v149, v149
	v_exp_f32_e32 v132, v132
	v_max_f32_e32 v134, 0x29e12e13, v133
	v_mul_f32_e32 v133, 0xbfb8aa3b, v84
	v_exp_f32_e32 v133, v133
	v_max_f32_e32 v158, 0x29e12e13, v149
	v_mul_f32_e32 v149, 0xbfb8aa3b, v81
	v_exp_f32_e32 v149, v149
	v_add_f32_e32 v133, 1.0, v133
	v_rcp_f32_e32 v133, v133
	v_add_f32_e32 v132, 1.0, v132
	v_add_f32_e32 v149, 1.0, v149
	v_rcp_f32_e32 v149, v149
	v_max_f32_e32 v156, 0x29e12e13, v133
	v_mul_f32_e32 v133, 0xbfb8aa3b, v80
	v_exp_f32_e32 v133, v133
	v_rcp_f32_e32 v132, v132
	v_rcp_f32_e32 v148, v156
	v_max_f32_e32 v159, 0x29e12e13, v149
	v_add_f32_e32 v133, 1.0, v133
	v_rcp_f32_e32 v133, v133
	v_rcp_f32_e32 v149, v158
	v_max_f32_e32 v132, 0x29e12e13, v132
	v_mul_f32_e32 v135, 0xbfb8aa3b, v89
	v_max_f32_e32 v157, 0x29e12e13, v133
	v_mul_f32_e32 v133, 0xbfb8aa3b, v93
	v_exp_f32_e32 v133, v133
	v_exp_f32_e32 v135, v135
	v_rcp_f32_e32 v150, v157
	v_rcp_f32_e32 v151, v159
	v_add_f32_e32 v133, 1.0, v133
	v_rcp_f32_e32 v133, v133
	v_add_f32_e32 v135, 1.0, v135
	v_rcp_f32_e32 v135, v135
	v_exp_f32_e32 v153, v153
	v_max_f32_e32 v133, 0x29e12e13, v133
	v_pk_mul_f32 v[132:133], v[148:149], v[132:133]
	v_mul_f32_e32 v149, 0xbfb8aa3b, v90
	v_exp_f32_e32 v149, v149
	v_max_f32_e32 v135, 0x29e12e13, v135
	v_pk_mul_f32 v[134:135], v[150:151], v[134:135]
	v_add_f32_e32 v153, 1.0, v153
	v_add_f32_e32 v149, 1.0, v149
	v_rcp_f32_e32 v149, v149
	v_rcp_f32_e32 v153, v153
	v_mul_f32_e32 v148, 0xbfb8aa3b, v94
	v_mul_f32_e32 v151, 0xbfb8aa3b, v91
	v_max_f32_e32 v150, 0x29e12e13, v149
	v_mul_f32_e32 v149, 0xbfb8aa3b, v86
	v_exp_f32_e32 v149, v149
	v_max_f32_e32 v166, 0x29e12e13, v153
	v_mul_f32_e32 v153, 0xbfb8aa3b, v83
	v_exp_f32_e32 v153, v153
	v_add_f32_e32 v149, 1.0, v149
	v_rcp_f32_e32 v149, v149
	v_exp_f32_e32 v148, v148
	v_exp_f32_e32 v151, v151
	v_add_f32_e32 v153, 1.0, v153
	v_max_f32_e32 v160, 0x29e12e13, v149
	v_mul_f32_e32 v149, 0xbfb8aa3b, v82
	v_exp_f32_e32 v149, v149
	v_rcp_f32_e32 v153, v153
	v_add_f32_e32 v148, 1.0, v148
	v_add_f32_e32 v151, 1.0, v151
	v_add_f32_e32 v149, 1.0, v149
	v_rcp_f32_e32 v149, v149
	v_rcp_f32_e32 v148, v148
	v_rcp_f32_e32 v151, v151
	v_max_f32_e32 v167, 0x29e12e13, v153
	v_max_f32_e32 v161, 0x29e12e13, v149
	v_mul_f32_e32 v149, 0xbfb8aa3b, v95
	v_exp_f32_e32 v149, v149
	v_rcp_f32_e32 v152, v160
	v_rcp_f32_e32 v154, v161
	v_rcp_f32_e32 v153, v166
	v_add_f32_e32 v149, 1.0, v149
	v_rcp_f32_e32 v149, v149
	v_rcp_f32_e32 v155, v167
	v_or_b32_e32 v147, 32, v146
	v_max_f32_e32 v148, 0x29e12e13, v148
	v_max_f32_e32 v149, 0x29e12e13, v149
	v_max_f32_e32 v151, 0x29e12e13, v151
	v_pk_mul_f32 v[148:149], v[152:153], v[148:149]
	v_pk_mul_f32 v[150:151], v[154:155], v[150:151]
	v_mad_i64_i32 v[152:153], s[6:7], v147, s33, v[128:129]
	v_cvt_pk_bf16_f32 v132, v132, v133
	v_cvt_pk_bf16_f32 v133, v148, v149
	v_cvt_pk_bf16_f32 v134, v134, v135
	v_cvt_pk_bf16_f32 v135, v150, v151
	v_lshl_add_u64 v[152:153], v[152:153], 0, v[130:131]
	v_cvt_pk_bf16_f32 v148, v156, v158
	v_cvt_pk_bf16_f32 v149, v160, v166
	v_cvt_pk_bf16_f32 v150, v157, v159
	v_cvt_pk_bf16_f32 v151, v161, v167
	global_store_dwordx4 v[152:153], v[132:135], off sc0 sc1
	global_store_dwordx4 v[152:153], v[148:151], off offset:2048 sc0 sc1
	v_mul_f32_e32 v153, 0xbfb8aa3b, v71
	v_mul_f32_e32 v133, 0xbfb8aa3b, v72
	v_exp_f32_e32 v133, v133
	v_mul_f32_e32 v149, 0xbfb8aa3b, v69
	v_exp_f32_e32 v149, v149
	v_mul_f32_e32 v132, 0xbfb8aa3b, v76
	v_add_f32_e32 v133, 1.0, v133
	v_rcp_f32_e32 v133, v133
	v_add_f32_e32 v149, 1.0, v149
	v_rcp_f32_e32 v149, v149
	v_exp_f32_e32 v132, v132
	v_max_f32_e32 v134, 0x29e12e13, v133
	v_mul_f32_e32 v133, 0xbfb8aa3b, v68
	v_exp_f32_e32 v133, v133
	v_max_f32_e32 v158, 0x29e12e13, v149
	v_mul_f32_e32 v149, 0xbfb8aa3b, v65
	v_exp_f32_e32 v149, v149
	v_add_f32_e32 v133, 1.0, v133
; __device__ __forceinline__ unsigned pk2(float lo, float hi) { f32v2 v = {lo, hi}; bf16v2 r = __builtin_convertvector(v, bf16v2); return __builtin_bit_cast(unsigned, r); }
; __device__ __forceinline__ float sigmoid_f(float x) { return __builtin_amdgcn_rcpf(1.0f + __builtin_amdgcn_exp2f(-1.4426950409f * x)); }
;     __device__ __forceinline__ void operator()(f32x4 (&acc)[2][2][4][2], const Unit& u, int wr, int wc, int fr, int fq) const {
;     ...
;             if (u.pn >= 6 && u.pn < 14) {
;                 const int chb = 128 * (u.pn - 6) + cl0;
; #pragma unroll
;                 for (int ai = 0; ai < 2; ++ai)
; #pragma unroll
;                     for (int m = 0; m < 4; ++m) {
;                         const size_t row = (size_t)(row0 + ai * HALF + m * 16);
;                         float r[8], g[8];
; #pragma unroll
;                         for (int e = 0; e < 4; ++e) {
;                             const float g0a = fmaxf(sigmoid_f(acc[ai][0][m][0][e]), 1e-13f), g0b = fmaxf(sigmoid_f(acc[ai][0][m][1][e]), 1e-13f);
;                             const float g1a = fmaxf(sigmoid_f(acc[ai][1][m][0][e]), 1e-13f), g1b = fmaxf(sigmoid_f(acc[ai][1][m][1][e]), 1e-13f);
;                             g[e] = g1a; g[4 + e] = g1b; r[e] = g0a * __builtin_amdgcn_rcpf(g1a); r[4 + e] = g0b * __builtin_amdgcn_rcpf(g1b);
;                         }
;                         u32x4 wr_, wg_; wr_.x = pk2(r[0], r[1]); wr_.y = pk2(r[2], r[3]); wr_.z = pk2(r[4], r[5]); wr_.w = pk2(r[6], r[7]);
;                         wg_.x = pk2(g[0], g[1]); wg_.y = pk2(g[2], g[3]); wg_.z = pk2(g[4], g[5]); wg_.w = pk2(g[6], g[7]);
;                         __builtin_nontemporal_store(wr_, (u32x4*)(O4 + row * 3072 + chb));
;                         __builtin_nontemporal_store(wg_, (u32x4*)(O4 + row * 3072 + 1024 + chb));
;                     }
	v_rcp_f32_e32 v133, v133
	v_add_f32_e32 v132, 1.0, v132
	v_add_f32_e32 v149, 1.0, v149
	v_rcp_f32_e32 v149, v149
	v_max_f32_e32 v156, 0x29e12e13, v133
	v_mul_f32_e32 v133, 0xbfb8aa3b, v64
	v_exp_f32_e32 v133, v133
	v_rcp_f32_e32 v132, v132
	v_rcp_f32_e32 v148, v156
	v_max_f32_e32 v159, 0x29e12e13, v149
	v_add_f32_e32 v133, 1.0, v133
	v_rcp_f32_e32 v133, v133
	v_rcp_f32_e32 v149, v158
	v_max_f32_e32 v132, 0x29e12e13, v132
	v_mul_f32_e32 v135, 0xbfb8aa3b, v73
	v_max_f32_e32 v157, 0x29e12e13, v133
	v_mul_f32_e32 v133, 0xbfb8aa3b, v77
	v_exp_f32_e32 v133, v133
	v_exp_f32_e32 v135, v135
	v_rcp_f32_e32 v150, v157
	v_rcp_f32_e32 v151, v159
	v_add_f32_e32 v133, 1.0, v133
	v_rcp_f32_e32 v133, v133
	v_add_f32_e32 v135, 1.0, v135
	v_rcp_f32_e32 v135, v135
	v_exp_f32_e32 v153, v153
	v_max_f32_e32 v133, 0x29e12e13, v133
	v_pk_mul_f32 v[132:133], v[148:149], v[132:133]
	v_mul_f32_e32 v149, 0xbfb8aa3b, v74
	v_exp_f32_e32 v149, v149
	v_max_f32_e32 v135, 0x29e12e13, v135
	v_pk_mul_f32 v[134:135], v[150:151], v[134:135]
	v_add_f32_e32 v153, 1.0, v153
	v_add_f32_e32 v149, 1.0, v149
	v_rcp_f32_e32 v149, v149
	v_rcp_f32_e32 v153, v153
	v_mul_f32_e32 v148, 0xbfb8aa3b, v78
	v_mul_f32_e32 v151, 0xbfb8aa3b, v75
	v_max_f32_e32 v150, 0x29e12e13, v149
	v_mul_f32_e32 v149, 0xbfb8aa3b, v70
	v_exp_f32_e32 v149, v149
	v_max_f32_e32 v166, 0x29e12e13, v153
	v_mul_f32_e32 v153, 0xbfb8aa3b, v67
	v_exp_f32_e32 v153, v153
	v_add_f32_e32 v149, 1.0, v149
	v_rcp_f32_e32 v149, v149
	v_exp_f32_e32 v148, v148
	v_exp_f32_e32 v151, v151
	v_add_f32_e32 v153, 1.0, v153
	v_max_f32_e32 v160, 0x29e12e13, v149
	v_mul_f32_e32 v149, 0xbfb8aa3b, v66
	v_exp_f32_e32 v149, v149
	v_rcp_f32_e32 v153, v153
	v_add_f32_e32 v148, 1.0, v148
	v_add_f32_e32 v151, 1.0, v151
	v_add_f32_e32 v149, 1.0, v149
	v_rcp_f32_e32 v149, v149
	v_rcp_f32_e32 v148, v148
	v_rcp_f32_e32 v151, v151
	v_max_f32_e32 v167, 0x29e12e13, v153
	v_max_f32_e32 v161, 0x29e12e13, v149
	v_mul_f32_e32 v149, 0xbfb8aa3b, v79
	v_exp_f32_e32 v149, v149
	v_rcp_f32_e32 v152, v160
	v_rcp_f32_e32 v154, v161
	v_rcp_f32_e32 v153, v166
	v_add_f32_e32 v149, 1.0, v149
	v_rcp_f32_e32 v149, v149
	v_rcp_f32_e32 v155, v167
	v_or_b32_e32 v147, 48, v146
	v_max_f32_e32 v148, 0x29e12e13, v148
	v_max_f32_e32 v149, 0x29e12e13, v149
	v_max_f32_e32 v151, 0x29e12e13, v151
	v_pk_mul_f32 v[148:149], v[152:153], v[148:149]
	v_pk_mul_f32 v[150:151], v[154:155], v[150:151]
	v_mad_i64_i32 v[152:153], s[6:7], v147, s33, v[128:129]
	v_cvt_pk_bf16_f32 v132, v132, v133
	v_cvt_pk_bf16_f32 v133, v148, v149
	v_cvt_pk_bf16_f32 v134, v134, v135
	v_cvt_pk_bf16_f32 v135, v150, v151
	v_lshl_add_u64 v[152:153], v[152:153], 0, v[130:131]
	v_cvt_pk_bf16_f32 v148, v156, v158
	v_cvt_pk_bf16_f32 v149, v160, v166
	v_cvt_pk_bf16_f32 v150, v157, v159
	v_cvt_pk_bf16_f32 v151, v161, v167
	global_store_dwordx4 v[152:153], v[132:135], off sc0 sc1
	global_store_dwordx4 v[152:153], v[148:151], off offset:2048 sc0 sc1
	v_mul_f32_e32 v153, 0xbfb8aa3b, v55
	v_mul_f32_e32 v133, 0xbfb8aa3b, v56
	v_exp_f32_e32 v133, v133
	v_mul_f32_e32 v149, 0xbfb8aa3b, v53
	v_exp_f32_e32 v149, v149
	v_mul_f32_e32 v132, 0xbfb8aa3b, v60
	v_add_f32_e32 v133, 1.0, v133
	v_rcp_f32_e32 v133, v133
	v_add_f32_e32 v149, 1.0, v149
	v_rcp_f32_e32 v149, v149
	v_exp_f32_e32 v132, v132
	v_max_f32_e32 v134, 0x29e12e13, v133
	v_mul_f32_e32 v133, 0xbfb8aa3b, v52
	v_exp_f32_e32 v133, v133
	v_max_f32_e32 v158, 0x29e12e13, v149
	v_mul_f32_e32 v149, 0xbfb8aa3b, v49
	v_exp_f32_e32 v149, v149
	v_add_f32_e32 v133, 1.0, v133
	v_rcp_f32_e32 v133, v133
	v_add_f32_e32 v132, 1.0, v132
	v_add_f32_e32 v149, 1.0, v149
	v_rcp_f32_e32 v149, v149
	v_max_f32_e32 v156, 0x29e12e13, v133
	v_mul_f32_e32 v133, 0xbfb8aa3b, v48
	v_exp_f32_e32 v133, v133
	v_rcp_f32_e32 v132, v132
	v_rcp_f32_e32 v148, v156
	v_max_f32_e32 v159, 0x29e12e13, v149
	v_add_f32_e32 v133, 1.0, v133
	v_rcp_f32_e32 v133, v133
	v_rcp_f32_e32 v149, v158
	v_max_f32_e32 v132, 0x29e12e13, v132
	v_mul_f32_e32 v135, 0xbfb8aa3b, v57
	v_max_f32_e32 v157, 0x29e12e13, v133
	v_mul_f32_e32 v133, 0xbfb8aa3b, v61
	v_exp_f32_e32 v133, v133
	v_exp_f32_e32 v135, v135
	v_rcp_f32_e32 v150, v157
	v_rcp_f32_e32 v151, v159
	v_add_f32_e32 v133, 1.0, v133
	v_rcp_f32_e32 v133, v133
	v_add_f32_e32 v135, 1.0, v135
	v_rcp_f32_e32 v135, v135
	v_exp_f32_e32 v153, v153
	v_max_f32_e32 v133, 0x29e12e13, v133
	v_pk_mul_f32 v[132:133], v[148:149], v[132:133]
	v_mul_f32_e32 v149, 0xbfb8aa3b, v58
	v_exp_f32_e32 v149, v149
	v_max_f32_e32 v135, 0x29e12e13, v135
	v_pk_mul_f32 v[134:135], v[150:151], v[134:135]
	v_add_f32_e32 v153, 1.0, v153
	v_add_f32_e32 v149, 1.0, v149
	v_rcp_f32_e32 v149, v149
	v_rcp_f32_e32 v153, v153
	v_mul_f32_e32 v148, 0xbfb8aa3b, v62
	v_mul_f32_e32 v151, 0xbfb8aa3b, v59
	v_max_f32_e32 v150, 0x29e12e13, v149
	v_mul_f32_e32 v149, 0xbfb8aa3b, v54
	v_exp_f32_e32 v149, v149
	v_max_f32_e32 v166, 0x29e12e13, v153
	v_mul_f32_e32 v153, 0xbfb8aa3b, v51
	v_exp_f32_e32 v153, v153
	v_add_f32_e32 v149, 1.0, v149
	v_rcp_f32_e32 v149, v149
	v_exp_f32_e32 v148, v148
	v_exp_f32_e32 v151, v151
	v_add_f32_e32 v153, 1.0, v153
	v_max_f32_e32 v160, 0x29e12e13, v149
	v_mul_f32_e32 v149, 0xbfb8aa3b, v50
	v_exp_f32_e32 v149, v149
	v_rcp_f32_e32 v153, v153
	v_add_f32_e32 v148, 1.0, v148
	v_add_f32_e32 v151, 1.0, v151
	v_add_f32_e32 v149, 1.0, v149
	v_rcp_f32_e32 v149, v149
	v_rcp_f32_e32 v148, v148
	v_rcp_f32_e32 v151, v151
	v_max_f32_e32 v167, 0x29e12e13, v153
	v_max_f32_e32 v161, 0x29e12e13, v149
	v_mul_f32_e32 v149, 0xbfb8aa3b, v63
	v_exp_f32_e32 v149, v149
	v_rcp_f32_e32 v152, v160
	v_rcp_f32_e32 v154, v161
	v_rcp_f32_e32 v153, v166
	v_add_f32_e32 v149, 1.0, v149
	v_rcp_f32_e32 v149, v149
	v_rcp_f32_e32 v155, v167
; __device__ __forceinline__ unsigned pk2(float lo, float hi) { f32v2 v = {lo, hi}; bf16v2 r = __builtin_convertvector(v, bf16v2); return __builtin_bit_cast(unsigned, r); }
; __device__ __forceinline__ float sigmoid_f(float x) { return __builtin_amdgcn_rcpf(1.0f + __builtin_amdgcn_exp2f(-1.4426950409f * x)); }
;     __device__ __forceinline__ void operator()(f32x4 (&acc)[2][2][4][2], const Unit& u, int wr, int wc, int fr, int fq) const {
;     ...
;             if (u.pn >= 6 && u.pn < 14) {
;                 const int chb = 128 * (u.pn - 6) + cl0;
; #pragma unroll
;                 for (int ai = 0; ai < 2; ++ai)
; #pragma unroll
;                     for (int m = 0; m < 4; ++m) {
;                         const size_t row = (size_t)(row0 + ai * HALF + m * 16);
;                         float r[8], g[8];
; #pragma unroll
;                         for (int e = 0; e < 4; ++e) {
;                             const float g0a = fmaxf(sigmoid_f(acc[ai][0][m][0][e]), 1e-13f), g0b = fmaxf(sigmoid_f(acc[ai][0][m][1][e]), 1e-13f);
;                             const float g1a = fmaxf(sigmoid_f(acc[ai][1][m][0][e]), 1e-13f), g1b = fmaxf(sigmoid_f(acc[ai][1][m][1][e]), 1e-13f);
;                             g[e] = g1a; g[4 + e] = g1b; r[e] = g0a * __builtin_amdgcn_rcpf(g1a); r[4 + e] = g0b * __builtin_amdgcn_rcpf(g1b);
;                         }
;                         u32x4 wr_, wg_; wr_.x = pk2(r[0], r[1]); wr_.y = pk2(r[2], r[3]); wr_.z = pk2(r[4], r[5]); wr_.w = pk2(r[6], r[7]);
;                         wg_.x = pk2(g[0], g[1]); wg_.y = pk2(g[2], g[3]); wg_.z = pk2(g[4], g[5]); wg_.w = pk2(g[6], g[7]);
;                         __builtin_nontemporal_store(wr_, (u32x4*)(O4 + row * 3072 + chb));
;                         __builtin_nontemporal_store(wg_, (u32x4*)(O4 + row * 3072 + 1024 + chb));
;                     }
	v_add_u32_e32 v147, 0x80, v146
	v_max_f32_e32 v148, 0x29e12e13, v148
	v_max_f32_e32 v149, 0x29e12e13, v149
	v_max_f32_e32 v151, 0x29e12e13, v151
	v_pk_mul_f32 v[148:149], v[152:153], v[148:149]
	v_pk_mul_f32 v[150:151], v[154:155], v[150:151]
	v_mad_i64_i32 v[152:153], s[6:7], v147, s33, v[128:129]
	v_cvt_pk_bf16_f32 v132, v132, v133
	v_cvt_pk_bf16_f32 v133, v148, v149
	v_cvt_pk_bf16_f32 v134, v134, v135
	v_cvt_pk_bf16_f32 v135, v150, v151
	v_lshl_add_u64 v[152:153], v[152:153], 0, v[130:131]
	v_cvt_pk_bf16_f32 v148, v156, v158
	v_cvt_pk_bf16_f32 v149, v160, v166
	v_cvt_pk_bf16_f32 v150, v157, v159
	v_cvt_pk_bf16_f32 v151, v161, v167
	global_store_dwordx4 v[152:153], v[132:135], off sc0 sc1
	global_store_dwordx4 v[152:153], v[148:151], off offset:2048 sc0 sc1
	v_mul_f32_e32 v153, 0xbfb8aa3b, v39
	v_mul_f32_e32 v133, 0xbfb8aa3b, v40
	v_exp_f32_e32 v133, v133
	v_mul_f32_e32 v149, 0xbfb8aa3b, v37
	v_exp_f32_e32 v149, v149
	v_mul_f32_e32 v132, 0xbfb8aa3b, v44
	v_add_f32_e32 v133, 1.0, v133
	v_rcp_f32_e32 v133, v133
	v_add_f32_e32 v149, 1.0, v149
	v_rcp_f32_e32 v149, v149
	v_exp_f32_e32 v132, v132
	v_max_f32_e32 v134, 0x29e12e13, v133
	v_mul_f32_e32 v133, 0xbfb8aa3b, v36
	v_exp_f32_e32 v133, v133
	v_max_f32_e32 v158, 0x29e12e13, v149
	v_mul_f32_e32 v149, 0xbfb8aa3b, v33
	v_exp_f32_e32 v149, v149
	v_add_f32_e32 v133, 1.0, v133
	v_rcp_f32_e32 v133, v133
	v_add_f32_e32 v132, 1.0, v132
	v_add_f32_e32 v149, 1.0, v149
	v_rcp_f32_e32 v149, v149
	v_max_f32_e32 v156, 0x29e12e13, v133
	v_mul_f32_e32 v133, 0xbfb8aa3b, v32
	v_exp_f32_e32 v133, v133
	v_rcp_f32_e32 v132, v132
	v_rcp_f32_e32 v148, v156
	v_max_f32_e32 v159, 0x29e12e13, v149
	v_add_f32_e32 v133, 1.0, v133
	v_rcp_f32_e32 v133, v133
	v_rcp_f32_e32 v149, v158
	v_max_f32_e32 v132, 0x29e12e13, v132
	v_mul_f32_e32 v135, 0xbfb8aa3b, v41
	v_max_f32_e32 v157, 0x29e12e13, v133
	v_mul_f32_e32 v133, 0xbfb8aa3b, v45
	v_exp_f32_e32 v133, v133
	v_exp_f32_e32 v135, v135
	v_rcp_f32_e32 v150, v157
	v_rcp_f32_e32 v151, v159
	v_add_f32_e32 v133, 1.0, v133
	v_rcp_f32_e32 v133, v133
	v_add_f32_e32 v135, 1.0, v135
	v_rcp_f32_e32 v135, v135
	v_exp_f32_e32 v153, v153
	v_max_f32_e32 v133, 0x29e12e13, v133
	v_pk_mul_f32 v[132:133], v[148:149], v[132:133]
	v_mul_f32_e32 v149, 0xbfb8aa3b, v42
	v_exp_f32_e32 v149, v149
	v_max_f32_e32 v135, 0x29e12e13, v135
	v_pk_mul_f32 v[134:135], v[150:151], v[134:135]
	v_add_f32_e32 v153, 1.0, v153
	v_add_f32_e32 v149, 1.0, v149
	v_rcp_f32_e32 v149, v149
	v_rcp_f32_e32 v153, v153
	v_mul_f32_e32 v148, 0xbfb8aa3b, v46
	v_mul_f32_e32 v151, 0xbfb8aa3b, v43
	v_max_f32_e32 v150, 0x29e12e13, v149
	v_mul_f32_e32 v149, 0xbfb8aa3b, v38
	v_exp_f32_e32 v149, v149
	v_max_f32_e32 v166, 0x29e12e13, v153
	v_mul_f32_e32 v153, 0xbfb8aa3b, v35
	v_exp_f32_e32 v153, v153
	v_add_f32_e32 v149, 1.0, v149
	v_rcp_f32_e32 v149, v149
	v_exp_f32_e32 v148, v148
	v_exp_f32_e32 v151, v151
	v_add_f32_e32 v153, 1.0, v153
	v_max_f32_e32 v160, 0x29e12e13, v149
	v_mul_f32_e32 v149, 0xbfb8aa3b, v34
	v_exp_f32_e32 v149, v149
	v_rcp_f32_e32 v153, v153
	v_add_f32_e32 v148, 1.0, v148
	v_add_f32_e32 v151, 1.0, v151
	v_add_f32_e32 v149, 1.0, v149
	v_rcp_f32_e32 v149, v149
	v_rcp_f32_e32 v148, v148
	v_rcp_f32_e32 v151, v151
	v_max_f32_e32 v167, 0x29e12e13, v153
	v_max_f32_e32 v161, 0x29e12e13, v149
	v_mul_f32_e32 v149, 0xbfb8aa3b, v47
	v_exp_f32_e32 v149, v149
	v_rcp_f32_e32 v152, v160
	v_rcp_f32_e32 v154, v161
	v_rcp_f32_e32 v153, v166
	v_add_f32_e32 v149, 1.0, v149
	v_rcp_f32_e32 v149, v149
	v_rcp_f32_e32 v155, v167
	v_add_u32_e32 v147, 0x90, v146
	v_max_f32_e32 v148, 0x29e12e13, v148
	v_max_f32_e32 v149, 0x29e12e13, v149
	v_max_f32_e32 v151, 0x29e12e13, v151
	v_pk_mul_f32 v[148:149], v[152:153], v[148:149]
	v_pk_mul_f32 v[150:151], v[154:155], v[150:151]
	v_mad_i64_i32 v[152:153], s[6:7], v147, s33, v[128:129]
	v_cvt_pk_bf16_f32 v132, v132, v133
	v_cvt_pk_bf16_f32 v133, v148, v149
	v_cvt_pk_bf16_f32 v134, v134, v135
	v_cvt_pk_bf16_f32 v135, v150, v151
	v_lshl_add_u64 v[152:153], v[152:153], 0, v[130:131]
	v_cvt_pk_bf16_f32 v148, v156, v158
	v_cvt_pk_bf16_f32 v149, v160, v166
	v_cvt_pk_bf16_f32 v150, v157, v159
	v_cvt_pk_bf16_f32 v151, v161, v167
	global_store_dwordx4 v[152:153], v[132:135], off sc0 sc1
	global_store_dwordx4 v[152:153], v[148:151], off offset:2048 sc0 sc1
	v_mul_f32_e32 v153, 0xbfb8aa3b, v23
	v_mul_f32_e32 v133, 0xbfb8aa3b, v24
	v_exp_f32_e32 v133, v133
	v_mul_f32_e32 v149, 0xbfb8aa3b, v21
	v_exp_f32_e32 v149, v149
	v_mul_f32_e32 v132, 0xbfb8aa3b, v28
	v_add_f32_e32 v133, 1.0, v133
	v_rcp_f32_e32 v133, v133
	v_add_f32_e32 v149, 1.0, v149
	v_rcp_f32_e32 v149, v149
	v_exp_f32_e32 v132, v132
	v_max_f32_e32 v134, 0x29e12e13, v133
	v_mul_f32_e32 v133, 0xbfb8aa3b, v20
	v_exp_f32_e32 v133, v133
	v_max_f32_e32 v158, 0x29e12e13, v149
	v_mul_f32_e32 v149, 0xbfb8aa3b, v17
	v_exp_f32_e32 v149, v149
	v_add_f32_e32 v133, 1.0, v133
	v_rcp_f32_e32 v133, v133
	v_add_f32_e32 v132, 1.0, v132
	v_add_f32_e32 v149, 1.0, v149
	v_rcp_f32_e32 v149, v149
	v_max_f32_e32 v156, 0x29e12e13, v133
	v_mul_f32_e32 v133, 0xbfb8aa3b, v16
	v_exp_f32_e32 v133, v133
	v_rcp_f32_e32 v132, v132
	v_rcp_f32_e32 v148, v156
	v_max_f32_e32 v159, 0x29e12e13, v149
	v_add_f32_e32 v133, 1.0, v133
	v_rcp_f32_e32 v133, v133
	v_rcp_f32_e32 v149, v158
	v_max_f32_e32 v132, 0x29e12e13, v132
	v_mul_f32_e32 v135, 0xbfb8aa3b, v25
	v_max_f32_e32 v157, 0x29e12e13, v133
	v_mul_f32_e32 v133, 0xbfb8aa3b, v29
	v_exp_f32_e32 v133, v133
	v_exp_f32_e32 v135, v135
	v_rcp_f32_e32 v150, v157
	v_rcp_f32_e32 v151, v159
	v_add_f32_e32 v133, 1.0, v133
	v_rcp_f32_e32 v133, v133
	v_add_f32_e32 v135, 1.0, v135
	v_rcp_f32_e32 v135, v135
	v_exp_f32_e32 v153, v153
; __device__ __forceinline__ unsigned pk2(float lo, float hi) { f32v2 v = {lo, hi}; bf16v2 r = __builtin_convertvector(v, bf16v2); return __builtin_bit_cast(unsigned, r); }
; __device__ __forceinline__ float sigmoid_f(float x) { return __builtin_amdgcn_rcpf(1.0f + __builtin_amdgcn_exp2f(-1.4426950409f * x)); }
;     __device__ __forceinline__ void operator()(f32x4 (&acc)[2][2][4][2], const Unit& u, int wr, int wc, int fr, int fq) const {
;     ...
;             if (u.pn >= 6 && u.pn < 14) {
;                 const int chb = 128 * (u.pn - 6) + cl0;
; #pragma unroll
;                 for (int ai = 0; ai < 2; ++ai)
; #pragma unroll
;                     for (int m = 0; m < 4; ++m) {
;                         const size_t row = (size_t)(row0 + ai * HALF + m * 16);
;                         float r[8], g[8];
; #pragma unroll
;                         for (int e = 0; e < 4; ++e) {
;                             const float g0a = fmaxf(sigmoid_f(acc[ai][0][m][0][e]), 1e-13f), g0b = fmaxf(sigmoid_f(acc[ai][0][m][1][e]), 1e-13f);
;                             const float g1a = fmaxf(sigmoid_f(acc[ai][1][m][0][e]), 1e-13f), g1b = fmaxf(sigmoid_f(acc[ai][1][m][1][e]), 1e-13f);
;                             g[e] = g1a; g[4 + e] = g1b; r[e] = g0a * __builtin_amdgcn_rcpf(g1a); r[4 + e] = g0b * __builtin_amdgcn_rcpf(g1b);
;                         }
;                         u32x4 wr_, wg_; wr_.x = pk2(r[0], r[1]); wr_.y = pk2(r[2], r[3]); wr_.z = pk2(r[4], r[5]); wr_.w = pk2(r[6], r[7]);
;                         wg_.x = pk2(g[0], g[1]); wg_.y = pk2(g[2], g[3]); wg_.z = pk2(g[4], g[5]); wg_.w = pk2(g[6], g[7]);
;                         __builtin_nontemporal_store(wr_, (u32x4*)(O4 + row * 3072 + chb));
;                         __builtin_nontemporal_store(wg_, (u32x4*)(O4 + row * 3072 + 1024 + chb));
;                     }
	v_max_f32_e32 v133, 0x29e12e13, v133
	v_pk_mul_f32 v[132:133], v[148:149], v[132:133]
	v_mul_f32_e32 v149, 0xbfb8aa3b, v26
	v_exp_f32_e32 v149, v149
	v_max_f32_e32 v135, 0x29e12e13, v135
	v_pk_mul_f32 v[134:135], v[150:151], v[134:135]
	v_add_f32_e32 v153, 1.0, v153
	v_add_f32_e32 v149, 1.0, v149
	v_rcp_f32_e32 v149, v149
	v_rcp_f32_e32 v153, v153
	v_mul_f32_e32 v148, 0xbfb8aa3b, v30
	v_mul_f32_e32 v151, 0xbfb8aa3b, v27
	v_max_f32_e32 v150, 0x29e12e13, v149
	v_mul_f32_e32 v149, 0xbfb8aa3b, v22
	v_exp_f32_e32 v149, v149
	v_max_f32_e32 v166, 0x29e12e13, v153
	v_mul_f32_e32 v153, 0xbfb8aa3b, v19
	v_exp_f32_e32 v153, v153
	v_add_f32_e32 v149, 1.0, v149
	v_rcp_f32_e32 v149, v149
	v_exp_f32_e32 v148, v148
	v_exp_f32_e32 v151, v151
	v_add_f32_e32 v153, 1.0, v153
	v_max_f32_e32 v160, 0x29e12e13, v149
	v_mul_f32_e32 v149, 0xbfb8aa3b, v18
	v_exp_f32_e32 v149, v149
	v_rcp_f32_e32 v153, v153
	v_add_f32_e32 v148, 1.0, v148
	v_add_f32_e32 v151, 1.0, v151
	v_add_f32_e32 v149, 1.0, v149
	v_rcp_f32_e32 v149, v149
	v_rcp_f32_e32 v148, v148
	v_rcp_f32_e32 v151, v151
	v_max_f32_e32 v167, 0x29e12e13, v153
	v_max_f32_e32 v161, 0x29e12e13, v149
	v_mul_f32_e32 v149, 0xbfb8aa3b, v31
	v_exp_f32_e32 v149, v149
	v_rcp_f32_e32 v152, v160
	v_rcp_f32_e32 v154, v161
	v_rcp_f32_e32 v153, v166
	v_add_f32_e32 v149, 1.0, v149
	v_rcp_f32_e32 v149, v149
	v_rcp_f32_e32 v155, v167
	v_add_u32_e32 v147, 0xa0, v146
	v_max_f32_e32 v148, 0x29e12e13, v148
	v_max_f32_e32 v149, 0x29e12e13, v149
	v_max_f32_e32 v151, 0x29e12e13, v151
	v_pk_mul_f32 v[148:149], v[152:153], v[148:149]
	v_pk_mul_f32 v[150:151], v[154:155], v[150:151]
	v_mad_i64_i32 v[152:153], s[6:7], v147, s33, v[128:129]
	v_cvt_pk_bf16_f32 v132, v132, v133
	v_cvt_pk_bf16_f32 v133, v148, v149
	v_cvt_pk_bf16_f32 v134, v134, v135
	v_cvt_pk_bf16_f32 v135, v150, v151
	v_lshl_add_u64 v[152:153], v[152:153], 0, v[130:131]
	v_cvt_pk_bf16_f32 v148, v156, v158
	v_cvt_pk_bf16_f32 v149, v160, v166
	v_cvt_pk_bf16_f32 v150, v157, v159
	v_cvt_pk_bf16_f32 v151, v161, v167
	global_store_dwordx4 v[152:153], v[132:135], off sc0 sc1
	global_store_dwordx4 v[152:153], v[148:151], off offset:2048 sc0 sc1
	v_mul_f32_e32 v153, 0xbfb8aa3b, v7
	v_mul_f32_e32 v133, 0xbfb8aa3b, v8
	v_exp_f32_e32 v133, v133
	v_mul_f32_e32 v149, 0xbfb8aa3b, v5
	v_exp_f32_e32 v149, v149
	v_mul_f32_e32 v132, 0xbfb8aa3b, v12
	v_add_f32_e32 v133, 1.0, v133
	v_rcp_f32_e32 v133, v133
	v_add_f32_e32 v149, 1.0, v149
	v_rcp_f32_e32 v149, v149
	v_exp_f32_e32 v132, v132
	v_max_f32_e32 v134, 0x29e12e13, v133
	v_mul_f32_e32 v133, 0xbfb8aa3b, v4
	v_exp_f32_e32 v133, v133
	v_max_f32_e32 v158, 0x29e12e13, v149
	v_mul_f32_e32 v149, 0xbfb8aa3b, v1
	v_exp_f32_e32 v149, v149
	v_add_f32_e32 v133, 1.0, v133
	v_rcp_f32_e32 v133, v133
	v_add_f32_e32 v132, 1.0, v132
	v_add_f32_e32 v149, 1.0, v149
	v_rcp_f32_e32 v149, v149
	v_max_f32_e32 v156, 0x29e12e13, v133
	v_mul_f32_e32 v133, 0xbfb8aa3b, v0
	v_exp_f32_e32 v133, v133
	v_rcp_f32_e32 v132, v132
	v_rcp_f32_e32 v148, v156
	v_max_f32_e32 v159, 0x29e12e13, v149
	v_add_f32_e32 v133, 1.0, v133
	v_rcp_f32_e32 v133, v133
	v_rcp_f32_e32 v149, v158
	v_max_f32_e32 v132, 0x29e12e13, v132
	v_mul_f32_e32 v135, 0xbfb8aa3b, v9
	v_max_f32_e32 v157, 0x29e12e13, v133
	v_mul_f32_e32 v133, 0xbfb8aa3b, v13
	v_exp_f32_e32 v133, v133
	v_exp_f32_e32 v135, v135
	v_rcp_f32_e32 v150, v157
	v_rcp_f32_e32 v151, v159
	v_add_f32_e32 v133, 1.0, v133
	v_rcp_f32_e32 v133, v133
	v_add_f32_e32 v135, 1.0, v135
	v_rcp_f32_e32 v135, v135
	v_exp_f32_e32 v153, v153
	v_max_f32_e32 v133, 0x29e12e13, v133
	v_pk_mul_f32 v[132:133], v[148:149], v[132:133]
	v_mul_f32_e32 v149, 0xbfb8aa3b, v10
	v_exp_f32_e32 v149, v149
	v_max_f32_e32 v135, 0x29e12e13, v135
	v_pk_mul_f32 v[134:135], v[150:151], v[134:135]
	v_add_f32_e32 v153, 1.0, v153
	v_add_f32_e32 v149, 1.0, v149
	v_rcp_f32_e32 v149, v149
	v_rcp_f32_e32 v153, v153
	v_mul_f32_e32 v148, 0xbfb8aa3b, v14
	v_mul_f32_e32 v151, 0xbfb8aa3b, v11
	v_max_f32_e32 v150, 0x29e12e13, v149
	v_mul_f32_e32 v149, 0xbfb8aa3b, v6
	v_exp_f32_e32 v149, v149
	v_max_f32_e32 v166, 0x29e12e13, v153
	v_mul_f32_e32 v153, 0xbfb8aa3b, v3
	v_exp_f32_e32 v153, v153
	v_add_f32_e32 v149, 1.0, v149
	v_rcp_f32_e32 v149, v149
	v_exp_f32_e32 v148, v148
	v_exp_f32_e32 v151, v151
	v_add_f32_e32 v153, 1.0, v153
	v_max_f32_e32 v160, 0x29e12e13, v149
	v_mul_f32_e32 v149, 0xbfb8aa3b, v2
	v_exp_f32_e32 v149, v149
	v_rcp_f32_e32 v153, v153
	v_add_f32_e32 v148, 1.0, v148
	v_add_f32_e32 v151, 1.0, v151
	v_add_f32_e32 v149, 1.0, v149
	v_rcp_f32_e32 v149, v149
	v_rcp_f32_e32 v148, v148
	v_rcp_f32_e32 v151, v151
	v_max_f32_e32 v167, 0x29e12e13, v153
	v_max_f32_e32 v161, 0x29e12e13, v149
	v_mul_f32_e32 v149, 0xbfb8aa3b, v15
	v_exp_f32_e32 v149, v149
	v_rcp_f32_e32 v152, v160
	v_rcp_f32_e32 v154, v161
	v_rcp_f32_e32 v153, v166
	v_add_f32_e32 v149, 1.0, v149
	v_rcp_f32_e32 v149, v149
	v_rcp_f32_e32 v155, v167
	v_add_u32_e32 v147, 0xb0, v146
	v_max_f32_e32 v148, 0x29e12e13, v148
	v_max_f32_e32 v149, 0x29e12e13, v149
	v_max_f32_e32 v151, 0x29e12e13, v151
	v_pk_mul_f32 v[148:149], v[152:153], v[148:149]
	v_pk_mul_f32 v[150:151], v[154:155], v[150:151]
	v_mad_i64_i32 v[128:129], s[6:7], v147, s33, v[128:129]
	v_cvt_pk_bf16_f32 v132, v132, v133
	v_cvt_pk_bf16_f32 v133, v148, v149
	v_cvt_pk_bf16_f32 v134, v134, v135
	v_cvt_pk_bf16_f32 v135, v150, v151
	v_lshl_add_u64 v[128:129], v[128:129], 0, v[130:131]
	v_cvt_pk_bf16_f32 v148, v156, v158
	v_cvt_pk_bf16_f32 v149, v160, v166
	v_cvt_pk_bf16_f32 v150, v157, v159
	v_cvt_pk_bf16_f32 v151, v161, v167
	global_store_dwordx4 v[128:129], v[132:135], off sc0 sc1
	global_store_dwordx4 v[128:129], v[148:151], off offset:2048 sc0 sc1
